# v16 plus static s_setprio 1 for waves 4-7 during attention unit
# speedup vs baseline: 1.0047x; 1.0012x over previous
.LBB0_960:
	s_lshl_b32 s4, s44, 8
	s_ashr_i32 s5, s4, 31
	s_lshl_b64 s[4:5], s[4:5], 1
	s_waitcnt lgkmcnt(0)
	s_add_u32 s19, s10, s4
	s_addc_u32 s25, s11, s5
	v_readlane_b32 s11, v254, 36
	v_cvt_pk_bf16_f32 v44, v57, v49
	v_cvt_pk_bf16_f32 v45, v56, v48
	v_cvt_pk_bf16_f32 v46, v53, v51
	v_cvt_pk_bf16_f32 v47, v52, v50
	v_ashrrev_i32_e32 v48, 5, v62
	s_nop 0
	v_add_u32_e32 v51, s11, v64
	v_xor_b32_e32 v52, v51, v62
	v_lshlrev_b32_e32 v51, 13, v51
	v_lshlrev_b32_e32 v52, 4, v52
	s_movk_i32 s34, 0xf0
	v_readlane_b32 s10, v254, 12
	v_and_or_b32 v227, v52, s34, v51
	v_bfe_u32 v49, v62, 2, 2
	v_add_u32_e32 v51, s10, v48
	v_ashrrev_i32_e32 v52, 2, v51
	v_lshrrev_b32_e32 v50, 1, v62
	v_lshlrev_b32_e32 v53, 3, v52
	v_and_or_b32 v49, v50, 8, v49
	v_and_b32_e32 v53, 0x7fff0, v53
	v_and_b32_e32 v51, 4, v51
	v_and_b32_e32 v50, 3, v62
	v_or3_b32 v51, v53, v51, v49
	v_lshlrev_b32_e32 v53, 6, v48
	v_lshlrev_b32_e32 v52, 1, v52
	v_and_b32_e32 v53, 0xc0, v53
	v_bitop3_b32 v52, v52, v50, 2 bitop3:0x6c
	v_lshl_or_b32 v52, v52, 4, v53
	v_readlane_b32 s10, v254, 37
	v_lshl_or_b32 v228, v51, 13, v52
	s_add_u32 s6, s19, 0x38000000
	v_add_u32_e32 v51, s10, v64
	v_xor_b32_e32 v52, v51, v62
	v_readlane_b32 s10, v254, 38
	v_lshlrev_b32_e32 v51, 13, v51
	v_lshlrev_b32_e32 v52, 4, v52
	v_add_u32_e32 v48, s10, v48
	v_and_or_b32 v229, v52, s34, v51
	v_ashrrev_i32_e32 v51, 2, v48
	s_addc_u32 s7, s25, 0
	v_lshlrev_b32_e32 v52, 3, v51
	v_and_b32_e32 v53, 4, v48
	v_lshlrev_b32_e32 v48, 6, v48
	v_lshlrev_b32_e32 v51, 1, v51
	s_add_u32 s4, s8, s4
	v_and_b32_e32 v52, 0x7fff0, v52
	v_and_b32_e32 v48, 0xc0, v48
	v_bitop3_b32 v50, v51, v50, 2 bitop3:0x6c
	s_addc_u32 s5, s9, s5
	v_ashrrev_i32_e32 v96, 3, v62
	v_or3_b32 v49, v52, v53, v49
	v_lshl_or_b32 v48, v50, 4, v48
	s_add_u32 s28, s4, 0x38000100
	v_lshl_or_b32 v231, v49, 13, v48
	v_add_u32_e32 v48, s11, v96
	s_addc_u32 s29, s5, 0
	v_lshlrev_b32_e32 v49, 4, v62
	v_lshlrev_b32_e32 v50, 3, v48
	s_add_u32 s8, s30, 0x34000000
	v_xor_b32_e32 v49, v50, v49
	v_lshlrev_b32_e32 v48, 7, v48
	s_movk_i32 s10, 0x70
	s_mov_b32 m0, s18
	s_addc_u32 s9, s31, 0
	v_and_or_b32 v232, v49, s10, v48
	s_mov_b64 s[10:11], s[6:7]
	s_waitcnt vmcnt(0)
	s_cmpk_lt_u32 s97, 0x1000
	s_cbranch_scc1 .Lmy_prio_skip
	s_setprio 1
.Lmy_prio_skip:
	s_add_i32 s34, s97, 0
	global_load_lds_dwordx4 v227, s[10:11]
	s_add_i32 m0, s18, 0x400
	v_lshlrev_b32_e32 v60, 8, v63
	global_load_lds_dwordx4 v229, s[10:11]
	s_add_i32 m0, s34, 0x4000
	v_and_b32_e32 v61, -16, v62
	global_load_lds_dwordx4 v232, s[8:9]
	s_add_u32 s8, s19, 0x38080000
	s_addc_u32 s9, s25, 0
	s_add_u32 s10, s30, 0x34002000
	s_addc_u32 s11, s31, 0
	s_add_i32 m0, s18, 0x6000
	v_lshlrev_b32_e32 v92, 4, v63
	global_load_lds_dwordx4 v227, s[8:9]
	s_add_i32 m0, s18, 0x6400
	v_xad_u32 v225, v92, v61, v60
	global_load_lds_dwordx4 v229, s[8:9]
	s_add_i32 m0, s34, 0xa000
	s_mov_b64 s[8:9], s[28:29]
	global_load_lds_dwordx4 v232, s[10:11]
	s_mov_b32 m0, s95
	v_add_u32_e32 v72, 0, v225
	global_load_lds_dwordx4 v228, s[8:9]
	s_add_i32 m0, s18, 0x12400
	v_add_u32_e32 v93, 64, v61
	global_load_lds_dwordx4 v231, s[8:9]
	s_add_u32 s8, s19, 0x38100000
	s_addc_u32 s9, s25, 0
	s_add_u32 s10, s30, 0x34004000
	s_waitcnt vmcnt(5)
	s_addc_u32 s11, s31, 0
	s_add_i32 m0, s18, 0xc000
	s_barrier
	v_xad_u32 v234, v93, v92, v60
	global_load_lds_dwordx4 v227, s[8:9]
	s_add_i32 m0, s18, 0xc400
	v_add_u32_e32 v94, 0, v234
	global_load_lds_dwordx4 v229, s[8:9]
	s_add_i32 m0, s34, 0x10000
	s_add_u32 s4, s4, 0x38080100
	global_load_lds_dwordx4 v232, s[10:11]
	s_addc_u32 s5, s5, 0
	s_add_i32 m0, s18, 0x16000
	v_lshlrev_b32_e32 v97, 3, v62
	global_load_lds_dwordx4 v228, s[4:5]
	s_add_i32 m0, s18, 0x16400
	s_mov_b32 s8, 0x3fffffc
	global_load_lds_dwordx4 v231, s[4:5]
	ds_read_b128 v[48:51], v72
	ds_read_b128 v[52:55], v72 offset:4096
	ds_read_b128 v[68:71], v72 offset:8192
	ds_read_b128 v[72:75], v72 offset:12288
	ds_read_b128 v[84:87], v94
	ds_read_b128 v[88:91], v94 offset:4096
	s_waitcnt lgkmcnt(0)
	v_mfma_f32_16x16x32_bf16 v[56:59], v[48:51], v[4:7], 0
	v_mov_b32_e32 v204, 1.0
	v_mov_b32_e32 v200, 0
	s_mov_b32 s25, 1
	v_mfma_f32_16x16x32_bf16 v[48:51], v[48:51], v[40:43], 0
	s_mov_b32 s4, 4
	s_mov_b32 s5, 2
	v_mov_b32_e32 v201, v200
	v_mfma_f32_16x16x32_bf16 v[64:67], v[52:55], v[4:7], 0
	v_mov_b32_e32 v205, v204
	v_mfma_f32_16x16x32_bf16 v[52:55], v[52:55], v[40:43], 0
	v_mfma_f32_16x16x32_bf16 v[76:79], v[68:71], v[4:7], 0
	v_mfma_f32_16x16x32_bf16 v[68:71], v[68:71], v[40:43], 0
	v_mfma_f32_16x16x32_bf16 v[56:59], v[84:87], v[0:3], v[56:59]
	v_mfma_f32_16x16x32_bf16 v[48:51], v[84:87], v[36:39], v[48:51]
	v_mfma_f32_16x16x32_bf16 v[64:67], v[88:91], v[0:3], v[64:67]
	v_mfma_f32_16x16x32_bf16 v[52:55], v[88:91], v[36:39], v[52:55]
	ds_read_b128 v[84:87], v94 offset:8192
	ds_read_b128 v[88:91], v94 offset:12288
	v_mfma_f32_16x16x32_bf16 v[80:83], v[72:75], v[4:7], 0
	v_mfma_f32_16x16x32_bf16 v[72:75], v[72:75], v[40:43], 0
	s_waitcnt lgkmcnt(0)
	v_mfma_f32_16x16x32_bf16 v[76:79], v[84:87], v[0:3], v[76:79]
	v_mfma_f32_16x16x32_bf16 v[68:71], v[84:87], v[36:39], v[68:71]
	v_add_u32_e32 v84, 0x80, v61
	v_xad_u32 v233, v84, v92, v60
	v_add_u32_e32 v94, 0, v233
	v_mfma_f32_16x16x32_bf16 v[80:83], v[88:91], v[0:3], v[80:83]
	v_mfma_f32_16x16x32_bf16 v[72:75], v[88:91], v[36:39], v[72:75]
	ds_read_b128 v[84:87], v94
	ds_read_b128 v[88:91], v94 offset:4096
	s_waitcnt lgkmcnt(0)
	v_mfma_f32_16x16x32_bf16 v[56:59], v[84:87], v[12:15], v[56:59]
	v_mfma_f32_16x16x32_bf16 v[48:51], v[84:87], v[28:31], v[48:51]
	v_mfma_f32_16x16x32_bf16 v[64:67], v[88:91], v[12:15], v[64:67]
	v_mfma_f32_16x16x32_bf16 v[52:55], v[88:91], v[28:31], v[52:55]
	ds_read_b128 v[84:87], v94 offset:8192
	ds_read_b128 v[88:91], v94 offset:12288
	s_waitcnt lgkmcnt(0)
	v_mfma_f32_16x16x32_bf16 v[76:79], v[84:87], v[12:15], v[76:79]
	v_mfma_f32_16x16x32_bf16 v[68:71], v[84:87], v[28:31], v[68:71]
	v_add_u32_e32 v84, 0xc0, v61
	v_xad_u32 v230, v84, v92, v60
	v_add_u32_e32 v60, 0, v230
	v_mfma_f32_16x16x32_bf16 v[80:83], v[88:91], v[12:15], v[80:83]
	v_and_b32_e32 v92, 0x70, v97
	v_mfma_f32_16x16x32_bf16 v[72:75], v[88:91], v[28:31], v[72:75]
	ds_read_b128 v[84:87], v60
	ds_read_b128 v[88:91], v60 offset:4096
	s_waitcnt lgkmcnt(0)
	v_mfma_f32_16x16x32_bf16 v[56:59], v[84:87], v[8:11], v[56:59]
	v_mfma_f32_16x16x32_bf16 v[48:51], v[84:87], v[24:27], v[48:51]
	v_mfma_f32_16x16x32_bf16 v[64:67], v[88:91], v[8:11], v[64:67]
	v_mfma_f32_16x16x32_bf16 v[52:55], v[88:91], v[24:27], v[52:55]
	ds_read_b128 v[84:87], v60 offset:8192
	ds_read_b128 v[88:91], v60 offset:12288
	v_lshlrev_b32_e32 v60, 7, v63
	v_xad_u32 v226, v92, v61, v60
	v_add_u32_e32 v61, 0, v226
	s_waitcnt lgkmcnt(0)
	v_mfma_f32_16x16x32_bf16 v[76:79], v[84:87], v[8:11], v[76:79]
	v_xad_u32 v224, v93, v92, v60
	v_add_u32_e32 v60, 0, v224
	v_mfma_f32_16x16x32_bf16 v[68:71], v[84:87], v[24:27], v[68:71]
	v_mfma_f32_16x16x32_bf16 v[80:83], v[88:91], v[8:11], v[80:83]
	v_mfma_f32_16x16x32_bf16 v[72:75], v[88:91], v[24:27], v[72:75]
	ds_read_b128 v[84:87], v61 offset:16384
	ds_read_b128 v[88:91], v61 offset:18432
	s_waitcnt lgkmcnt(0)
	v_mfma_f32_16x16x32_bf16 v[56:59], v[84:87], v[16:19], v[56:59]
	v_mfma_f32_16x16x32_bf16 v[48:51], v[84:87], v[32:35], v[48:51]
	v_mfma_f32_16x16x32_bf16 v[64:67], v[88:91], v[16:19], v[64:67]
	v_mfma_f32_16x16x32_bf16 v[52:55], v[88:91], v[32:35], v[52:55]
	ds_read_b128 v[84:87], v61 offset:20480
	ds_read_b128 v[88:91], v61 offset:22528
	v_lshrrev_b32_e32 v61, 2, v63
	v_and_or_b32 v61, v96, s8, v61
	s_waitcnt lgkmcnt(0)
	v_mfma_f32_16x16x32_bf16 v[76:79], v[84:87], v[16:19], v[76:79]
	s_mov_b32 s8, 0
	s_mov_b32 s10, s8
	s_mov_b32 s11, s8
	v_mfma_f32_16x16x32_bf16 v[68:71], v[84:87], v[32:35], v[68:71]
	s_mov_b32 s9, s8
	v_mfma_f32_16x16x32_bf16 v[80:83], v[88:91], v[16:19], v[80:83]
	v_mfma_f32_16x16x32_bf16 v[72:75], v[88:91], v[32:35], v[72:75]
	ds_read_b128 v[84:87], v60 offset:16384
	ds_read_b128 v[88:91], v60 offset:18432
	s_waitcnt lgkmcnt(0)
	v_mfma_f32_16x16x32_bf16 v[56:59], v[84:87], v[20:23], v[56:59]
	v_mfma_f32_16x16x32_bf16 v[84:87], v[84:87], v[44:47], v[48:51]
	s_nop 2
	ds_read_b128 v[48:51], v60 offset:20480
	v_mfma_f32_16x16x32_bf16 v[92:95], v[88:91], v[44:47], v[52:55]
	s_nop 2
	ds_read_b128 v[52:55], v60 offset:22528
	v_bfe_u32 v60, v62, 4, 1
	v_lshlrev_b32_e32 v63, 11, v60
	s_waitcnt lgkmcnt(0)
	v_mfma_f32_16x16x32_bf16 v[76:79], v[48:51], v[20:23], v[76:79]
	v_mfma_f32_16x16x32_bf16 v[68:71], v[48:51], v[44:47], v[68:71]
	v_lshl_add_u32 v48, v61, 6, v63
	v_and_or_b32 v48, v97, 24, v48
	v_lshlrev_b32_e32 v49, 5, v60
	v_mfma_f32_16x16x32_bf16 v[64:67], v[88:91], v[20:23], v[64:67]
	v_or_b32_e32 v223, v48, v49
	v_bitop3_b32 v222, v48, 32, v49 bitop3:0x36
	v_max_f32_e32 v48, v85, v85
	v_max_f32_e32 v49, v84, v84
	v_max_f32_e32 v48, v49, v48
	v_max_f32_e32 v49, v57, v57
	v_max_f32_e32 v50, v56, v56
	v_max_f32_e32 v49, v50, v49
	v_max3_f32 v48, v48, v86, v87
	v_max3_f32 v49, v49, v58, v59
	v_mfma_f32_16x16x32_bf16 v[80:83], v[52:55], v[20:23], v[80:83]
	v_max3_f32 v48, v48, v92, v93
	v_max3_f32 v49, v49, v64, v65
	v_max3_f32 v48, v48, v94, v95
	v_mfma_f32_16x16x32_bf16 v[72:75], v[52:55], v[44:47], v[72:75]
	v_max3_f32 v49, v49, v66, v67
	v_max3_f32 v48, v48, v68, v69
	v_max3_f32 v49, v49, v76, v77
	v_max3_f32 v48, v48, v70, v71
	v_max3_f32 v49, v49, v78, v79
	s_nop 2
	v_max3_f32 v48, v48, v72, v73
	v_max3_f32 v49, v49, v80, v81
	v_lshlrev_b32_e32 v50, 2, v62
	v_max3_f32 v48, v48, v74, v75
	v_max3_f32 v49, v49, v82, v83
	v_xor_b32_e32 v220, 64, v50
	ds_bpermute_b32 v51, v220, v49
	ds_bpermute_b32 v52, v220, v48
	v_xor_b32_e32 v221, 0x80, v50
	v_mov_b64_e32 v[90:91], s[10:11]
	v_mov_b64_e32 v[88:89], s[8:9]
	s_waitcnt lgkmcnt(0)
	v_max_f32_e32 v50, v51, v51
	v_max_f32_e32 v51, v52, v52
	v_max_f32_e32 v48, v48, v51
	ds_bpermute_b32 v51, v221, v48
	v_max_f32_e32 v49, v49, v50
	ds_bpermute_b32 v50, v221, v49
	s_add_u32 s10, s30, 0x34008000
	v_mov_b64_e32 v[102:103], v[90:91]
	s_waitcnt lgkmcnt(0)
	v_max_f32_e32 v51, v51, v51
	v_max_f32_e32 v51, v48, v51
	v_max_f32_e32 v48, v50, v50
	v_max_f32_e32 v50, v49, v48
	v_pk_add_f32 v[202:203], v[50:51], 0 op_sel_hi:[1,0]
	v_sub_f32_e32 v53, v94, v51
	v_pk_add_f32 v[48:49], v[202:203], 0 neg_lo:[1,1] neg_hi:[1,1]
	v_sub_f32_e32 v54, v93, v51
	v_sub_f32_e32 v49, v95, v51
	v_exp_f32_e32 v137, v54
	v_exp_f32_e32 v138, v53
	v_exp_f32_e32 v139, v49
	v_sub_f32_e32 v49, v67, v50
	v_sub_f32_e32 v53, v66, v50
	v_sub_f32_e32 v54, v65, v50
	v_sub_f32_e32 v131, v75, v51
	v_sub_f32_e32 v130, v74, v51
	v_sub_f32_e32 v129, v73, v51
	v_sub_f32_e32 v128, v72, v51
	v_sub_f32_e32 v143, v71, v51
	v_sub_f32_e32 v142, v70, v51
	v_sub_f32_e32 v141, v69, v51
	v_sub_f32_e32 v140, v68, v51
	v_sub_f32_e32 v55, v92, v51
	v_exp_f32_e32 v153, v54
	v_exp_f32_e32 v154, v53
	v_exp_f32_e32 v155, v49
	v_sub_f32_e32 v49, v87, v51
	v_sub_f32_e32 v53, v86, v51
	v_sub_f32_e32 v54, v85, v51
	v_sub_f32_e32 v51, v84, v51
	v_sub_f32_e32 v135, v83, v50
	v_sub_f32_e32 v134, v82, v50
	v_sub_f32_e32 v133, v81, v50
	v_sub_f32_e32 v132, v80, v50
	v_sub_f32_e32 v151, v79, v50
	v_sub_f32_e32 v150, v78, v50
	v_sub_f32_e32 v149, v77, v50
	v_sub_f32_e32 v148, v76, v50
	v_exp_f32_e32 v136, v55
	v_sub_f32_e32 v55, v64, v50
	v_exp_f32_e32 v144, v51
	v_exp_f32_e32 v146, v53
	v_exp_f32_e32 v147, v49
	v_sub_f32_e32 v49, v59, v50
	v_sub_f32_e32 v51, v58, v50
	v_sub_f32_e32 v53, v57, v50
	v_sub_f32_e32 v50, v56, v50
	v_exp_f32_e32 v152, v55
	v_exp_f32_e32 v145, v54
	v_exp_f32_e32 v156, v50
	v_exp_f32_e32 v157, v53
	v_exp_f32_e32 v158, v51
	v_exp_f32_e32 v159, v49
	v_xor_b32_e32 v52, 0x80000000, v203
	v_mov_b64_e32 v[106:107], v[90:91]
	v_mov_b64_e32 v[118:119], v[90:91]
	v_mov_b64_e32 v[56:57], v[88:89]
	v_mov_b64_e32 v[64:65], v[88:89]
	v_mov_b64_e32 v[72:73], v[88:89]
	v_mov_b64_e32 v[80:81], v[88:89]
	v_mov_b64_e32 v[94:95], v[90:91]
	v_mov_b64_e32 v[98:99], v[90:91]
	v_mov_b64_e32 v[110:111], v[90:91]
	v_mov_b64_e32 v[114:115], v[90:91]
	v_mov_b64_e32 v[84:85], v[88:89]
	v_mov_b64_e32 v[76:77], v[88:89]
	v_mov_b64_e32 v[68:69], v[88:89]
	v_mov_b64_e32 v[60:61], v[88:89]
	s_addc_u32 s11, s31, 0
	s_mov_b64 s[30:31], 0
	v_mov_b64_e32 v[100:101], v[88:89]
	v_mov_b64_e32 v[104:105], v[88:89]
	v_mov_b64_e32 v[116:117], v[88:89]
	v_mov_b64_e32 v[58:59], v[90:91]
	v_mov_b64_e32 v[66:67], v[90:91]
	v_mov_b64_e32 v[74:75], v[90:91]
	v_mov_b64_e32 v[82:83], v[90:91]
	v_mov_b64_e32 v[92:93], v[88:89]
	v_mov_b64_e32 v[96:97], v[88:89]
	v_mov_b64_e32 v[108:109], v[88:89]
	v_mov_b64_e32 v[112:113], v[88:89]
	v_mov_b64_e32 v[86:87], v[90:91]
	v_mov_b64_e32 v[78:79], v[90:91]
	v_mov_b64_e32 v[70:71], v[90:91]
	v_mov_b64_e32 v[62:63], v[90:91]
	v_mov_b32_e32 v53, v52
	v_mov_b32_e32 v54, v52
	v_mov_b32_e32 v55, v52
	v_mov_b32_e32 v49, v48
	v_mov_b32_e32 v50, v48
	v_mov_b32_e32 v51, v48
